# v8
# speedup vs baseline: 1.0021x; 1.0021x over previous
; DEVI void phase_mix(const Params& p, char* lds) {
;   const int NSSD = (32 + 32 * 16) / 2, NATT = 5120;
;   int* su = (int*)(lds + LDS_UNIT_OFF);
;   for (;;) {
;     __syncthreads();
;     if (threadIdx.x == 0) *su = (int)atomicAdd(P_COUNTER, 1u);
;     __syncthreads();
;     const int u = *su;
;     if (u >= NSSD + NATT) break;
.LBB0_172:
	v_writelane_b32 v255, s60, 19
	v_writelane_b32 v255, s58, 20
	s_nop 1
	v_writelane_b32 v255, s59, 21
	v_writelane_b32 v255, s92, 22
	s_nop 1
	v_writelane_b32 v255, s93, 23
	v_writelane_b32 v255, s88, 24
	v_writelane_b32 v255, s72, 25
	s_nop 1
	v_writelane_b32 v255, s73, 26
	v_writelane_b32 v255, s74, 27
	v_writelane_b32 v255, s75, 28
	v_writelane_b32 v255, s76, 29
	v_writelane_b32 v255, s77, 30
	v_writelane_b32 v255, s78, 31
	v_writelane_b32 v255, s79, 32
	v_writelane_b32 v255, s80, 33
	v_writelane_b32 v255, s81, 34
	v_writelane_b32 v255, s82, 35
	v_writelane_b32 v255, s83, 36
	v_writelane_b32 v255, s84, 37
	v_writelane_b32 v255, s85, 38
	v_writelane_b32 v255, s86, 39
	v_writelane_b32 v255, s87, 40
	s_or_b64 exec, exec, s[0:1]
	s_add_u32 s0, s90, 0x1f80000
	s_addc_u32 s1, s91, 0
	s_add_u32 s56, s90, 0xcfa4000
	v_writelane_b32 v255, s0, 41
	s_addc_u32 s57, s91, 0
	v_cmp_eq_u32_e64 s[24:25], 0, v164
	v_writelane_b32 v255, s1, 42
	s_add_u32 s0, s90, 0x1f80100
	s_addc_u32 s1, s91, 0
	v_writelane_b32 v255, s0, 43
	v_mbcnt_hi_u32_b32 v165, -1, v144
	s_mov_b32 s26, 0x41800000
	v_writelane_b32 v255, s1, 44
	s_add_u32 s0, s90, 0x2764000
	s_addc_u32 s1, s91, 0
	v_writelane_b32 v255, s0, 45
	s_mov_b32 s30, 2.0
	s_mov_b32 s96, 0x41900000
	v_writelane_b32 v255, s1, 46
	s_add_u32 s0, s90, 0x1f80c00
	s_addc_u32 s1, s91, 0
	v_writelane_b32 v255, s0, 47
	s_mov_b32 s98, 0x42000000
	s_mov_b32 s88, 0x42080000
	v_writelane_b32 v255, s1, 48
	s_add_u32 s0, s90, 0xcfa6400
	s_addc_u32 s1, s91, 0
	v_writelane_b32 v255, s0, 49
	s_mov_b32 s82, 0x42480000
	v_and_b32_e32 v175, 64, v165
	v_writelane_b32 v255, s1, 50
	s_add_u32 s0, s90, 0x3ca18200
	s_addc_u32 s1, s91, 0
	v_writelane_b32 v255, s0, 51
	s_mov_b32 s77, 0
	v_mov_b32_e32 v1, 0
	v_writelane_b32 v255, s1, 52
	s_mov_b32 s0, 0x42400000
	v_writelane_b32 v255, s24, 53
	v_mov_b32_e32 v173, 0x24800
	s_movk_i32 s33, 0x2440
	s_mov_b32 s27, 0x41880000
	s_mov_b64 s[28:29], 0x2000
	s_mov_b32 s31, 0x40400000
	s_mov_b32 s97, 0x41980000
	s_mov_b32 s99, 0x42040000
	s_mov_b32 s89, 0x420c0000
	s_mov_b32 s1, 0x42440000
	s_mov_b32 s83, 0x424c0000
	v_mov_b32_e32 v174, 0x15000
	s_mov_b32 s84, 0xcfa6000
	s_mov_b64 s[78:79], 0xcfa6000
	s_mov_b64 s[80:81], 0xcfa5800
	s_movk_i32 s85, 0x7fff
	s_mov_b32 s86, 0x5040100
	v_add_u32_e32 v166, 64, v175
	v_mov_b32_e32 v176, 0x2440
	v_mov_b32_e32 v122, 0x3f317218
	v_writelane_b32 v255, s25, 54
	v_readlane_b32 s100, v255, 2
	s_mov_b32 s101, 0
	s_barrier
	s_branch .LBB0_176

; DEVI void phase_mix(const Params& p, char* lds) {
;     ...
;   for (;;) {
;     __syncthreads();
;     if (threadIdx.x == 0) *su = (int)atomicAdd(P_COUNTER, 1u);
;     __syncthreads();
;     const int u = *su;
;     if (u >= NSSD + NATT) break;
;     if (u < NSSD) ssd_unit(p, lds, u);
;     else attn_unit(p, lds, u - NSSD);
.LBB0_176:
	s_barrier
	s_and_saveexec_b64 s[2:3], s[24:25]
	s_cbranch_execz .LBB0_180
	v_readlane_b32 s6, v255, 41
	v_readlane_b32 s7, v255, 42
	s_waitcnt vmcnt(0)
.Lq_fetch:
	s_lshl_b32 s4, s100, 6
	s_addk_i32 s4, 0x400
	v_mov_b32_e32 v0, s4
	v_mov_b32_e32 v2, 1
	s_nop 4
	global_atomic_add v2, v0, v2, s[6:7] sc0
	s_waitcnt vmcnt(0)
	v_readfirstlane_b32 s4, v2
	s_nop 3
	s_cmpk_lt_u32 s4, 0x2a2
	s_cbranch_scc1 .Lq_valid
	s_add_i32 s100, s100, 1
	s_and_b32 s100, s100, 7
	s_add_i32 s101, s101, 1
	s_cmpk_lt_u32 s101, 8
	s_cbranch_scc1 .Lq_fetch
	s_movk_i32 s5, 0x1510
	s_branch .Lq_done
.Lq_valid:
	s_cmpk_lt_u32 s4, 2
	s_cbranch_scc0 .Lq_a
	s_lshl_b32 s5, s100, 1
	s_add_i32 s5, s5, s4
	s_branch .Lq_done
.Lq_a:
	s_cmpk_lt_u32 s4, 34
	s_cbranch_scc0 .Lq_b
	s_lshl_b32 s5, s100, 5
	s_add_i32 s5, s5, s4
	s_addk_i32 s5, 14
	s_branch .Lq_done
.Lq_b:
	s_cmpk_lt_u32 s4, 0xa2
	s_cbranch_scc0 .Lq_c
	s_add_i32 s4, s4, 0xffffffde
	s_lshr_b32 s5, s4, 4
	s_lshl_b32 s5, s5, 7
	s_and_b32 s4, s4, 15
	s_add_i32 s5, s5, s4
	s_lshl_b32 s4, s100, 4
	s_add_i32 s5, s5, s4
	s_addk_i32 s5, 0x110
	s_branch .Lq_done
.Lq_c:
	s_add_i32 s4, s4, 0xffffff5e
	s_lshr_b32 s5, s4, 4
	s_and_b32 s5, s5, 3
	s_lshl_b32 s6, s100, 2
	s_add_i32 s5, s5, s6
	s_lshl_b32 s5, s5, 7
	s_lshr_b32 s6, s4, 6
	s_lshl_b32 s6, s6, 4
	s_add_i32 s5, s5, s6
	s_and_b32 s4, s4, 15
	s_add_i32 s5, s5, s4
	s_addk_i32 s5, 0x510
.Lq_done:
	v_mov_b32_e32 v0, s5
	ds_write_b32 v173, v0

; DEVI void phase_norm2(const Params& p) {
;   int tid0_ = threadIdx.x;
;   asm volatile("" : "+v"(tid0_));
;   const int lane = tid0_ & 63, wid = tid0_ >> 6;
;   const int stride = gridDim.x * 8;
;   for (int o0 = blockIdx.x * 8 + wid; o0 < OROWS; o0 += stride * 4) {
;     float4 v[4][4];
; #pragma unroll
;     for (int u = 0; u < 4; ++u) {
;       const int o = (o0 + u * stride < OROWS) ? o0 + u * stride : o0;
;       const float* src = p.out + (size_t)o * 1024;
; #pragma unroll
;       for (int j = 0; j < 4; ++j) v[u][j] = *(const float4*)(src + (j * 64 + lane) * 4);
;     }
;     ...
;           float4 w = *(const float4*)(p.norm2_w + (j * 64 + lane) * 4);
.LBB0_333:
	s_or_b64 exec, exec, s[2:3]
	v_mov_b32_e32 v0, v164
	s_barrier
	s_mov_b32 s1, 0x14000
	v_ashrrev_i32_e32 v1, 6, v0
	v_add_u32_e32 v48, s65, v1
	s_lshl_b32 s38, s64, 3
	v_cmp_gt_i32_e32 vcc, s1, v48
	s_mul_i32 s39, s64, 24
	s_and_saveexec_b64 s[10:11], vcc
	s_cbranch_execz .LBB0_342
	v_xor_b32_e32 v2, 32, v165
	v_cmp_lt_i32_e32 vcc, v2, v166
	v_lshlrev_b32_e32 v1, 2, v0
	v_and_b32_e32 v1, 0xfc, v1
	v_cndmask_b32_e32 v2, v165, v2, vcc
	v_lshlrev_b32_e32 v68, 2, v2
	v_xor_b32_e32 v2, 16, v165
	v_cmp_lt_i32_e32 vcc, v2, v166
	v_lshlrev_b32_e32 v50, 2, v1
	v_mov_b32_e32 v51, 0
	v_cndmask_b32_e32 v2, v165, v2, vcc
	v_lshlrev_b32_e32 v69, 2, v2
	v_xor_b32_e32 v2, 8, v165
	v_cmp_lt_i32_e32 vcc, v2, v166
	v_lshl_add_u64 v[52:53], s[54:55], 0, v[50:51]
	v_lshl_add_u64 v[54:55], s[62:63], 0, v[50:51]
	v_cndmask_b32_e32 v2, v165, v2, vcc
	v_lshlrev_b32_e32 v70, 2, v2
	v_xor_b32_e32 v2, 4, v165
	v_cmp_lt_i32_e32 vcc, v2, v166
	v_lshlrev_b32_e32 v50, 1, v1
	v_ashrrev_i32_e32 v49, 31, v48
	v_cndmask_b32_e32 v2, v165, v2, vcc
	v_lshlrev_b32_e32 v71, 2, v2
	v_xor_b32_e32 v2, 2, v165
	v_cmp_lt_i32_e32 vcc, v2, v166
	s_lshl_b32 s12, s64, 5
	s_ashr_i32 s13, s12, 31
	v_cndmask_b32_e32 v2, v165, v2, vcc
	v_lshlrev_b32_e32 v72, 2, v2
	v_xor_b32_e32 v2, 1, v165
	v_cmp_lt_i32_e32 vcc, v2, v166
	s_mov_b64 s[2:3], 0x800
	v_lshl_add_u64 v[56:57], s[88:89], 0, v[50:51]
	v_cndmask_b32_e32 v2, v165, v2, vcc
	v_lshlrev_b32_e32 v73, 2, v2
	v_and_b32_e32 v2, 63, v0
	v_add_u32_e32 v0, s38, v48
	v_ashrrev_i32_e32 v1, 31, v0
	v_lshlrev_b64 v[0:1], 11, v[0:1]
	v_lshl_add_u64 v[58:59], s[90:91], 0, v[0:1]
	v_lshlrev_b64 v[0:1], 11, v[48:49]
	v_lshl_add_u64 v[60:61], s[90:91], 0, v[0:1]
	v_lshlrev_b64 v[0:1], 12, v[48:49]
	v_lshl_or_b32 v0, v2, 4, v0
	v_lshl_add_u64 v[0:1], s[62:63], 0, v[0:1]
	s_lshl_b32 s22, s64, 4
	v_lshlrev_b32_e32 v50, 3, v2
	s_lshl_b64 s[14:15], s[12:13], 11
	v_lshl_add_u64 v[62:63], v[0:1], 0, s[2:3]
	s_lshl_b64 s[16:17], s[12:13], 12
	s_mov_b64 s[18:19], 0
	v_mov_b32_e32 v49, 0x3727c5ac
	s_mov_b32 s13, 0x800000
	s_mov_b32 s23, 0x2764000
	s_mov_b32 s24, 0x13fff
	global_load_dwordx4 v[104:107], v[52:53], off
	global_load_dwordx4 v[108:111], v[52:53], off offset:1024
	global_load_dwordx4 v[112:115], v[52:53], off offset:2048
	global_load_dwordx4 v[116:119], v[52:53], off offset:3072
	s_branch .LBB0_336

; DEVI void phase_norm2(const Params& p) {
;     ...
;   for (int o0 = blockIdx.x * 8 + wid; o0 < OROWS; o0 += stride * 4) {
;     float4 v[4][4];
; #pragma unroll
;     for (int u = 0; u < 4; ++u) {
;       const int o = (o0 + u * stride < OROWS) ? o0 + u * stride : o0;
;       const float* src = p.out + (size_t)o * 1024;
; #pragma unroll
;       for (int j = 0; j < 4; ++j) v[u][j] = *(const float4*)(src + (j * 64 + lane) * 4);
;     }
; #pragma unroll
;     for (int u = 0; u < 4; ++u) {
;       const int o = o0 + u * stride;
;       float ss = 0.f;
; #pragma unroll
;       for (int j = 0; j < 4; ++j) ss += v[u][j].x * v[u][j].x + v[u][j].y * v[u][j].y + v[u][j].z * v[u][j].z + v[u][j].w * v[u][j].w;
;       ss = wsum(ss);
;       float rs = rsqrtf(ss * (1.f / 1024.f) + EPSN);
;       if (o < OROWS) {
; #pragma unroll
;         for (int j = 0; j < 4; ++j) {
;           float4 w = *(const float4*)(p.norm2_w + (j * 64 + lane) * 4);
;           uint2 ov;
;           ov.x = pk2(v[u][j].x * rs * w.x, v[u][j].y * rs * w.y);
;           ov.y = pk2(v[u][j].z * rs * w.z, v[u][j].w * rs * w.w);
;           *(uint2*)(P_U2 + (size_t)o * 1024 + (j * 64 + lane) * 4) = ov;
;         }
;       }
;     }
.LBB0_336:
	global_load_dwordx4 v[74:77], v[62:63], off offset:-2048
	global_load_dwordx4 v[78:81], v[62:63], off offset:-1024
	global_load_dwordx4 v[82:85], v[62:63], off
	global_load_dwordx4 v[86:89], v[62:63], off offset:1024
	v_add_u32_e32 v2, s38, v48
	v_add_u32_e32 v66, s22, v48
	v_add_u32_e32 v64, s39, v48
	v_cmp_gt_i32_e64 s[4:5], s1, v2
	v_cmp_gt_i32_e64 s[2:3], s1, v66
	v_cmp_gt_i32_e32 vcc, s1, v64
	v_lshl_add_u64 v[0:1], v[60:61], 0, v[50:51]
	v_cndmask_b32_e64 v2, v48, v2, s[4:5]
	v_add_co_u32_e64 v94, s[6:7], s23, v0
	s_waitcnt vmcnt(3)
	v_mov_b32_e32 v10, v75
	s_waitcnt vmcnt(2)
	v_mov_b32_e32 v11, v79
	v_mov_b32_e32 v8, v74
	v_mov_b32_e32 v9, v78
	s_waitcnt vmcnt(1)
	v_mov_b32_e32 v18, v83
	s_waitcnt vmcnt(0)
	v_mov_b32_e32 v19, v87
	v_pk_mul_f32 v[10:11], v[10:11], v[10:11]
	v_mov_b32_e32 v4, v76
	v_mov_b32_e32 v5, v80
	v_mov_b32_e32 v16, v82
	s_waitcnt lgkmcnt(0)
	v_mov_b32_e32 v17, v86
	v_pk_mul_f32 v[18:19], v[18:19], v[18:19]
	v_pk_fma_f32 v[8:9], v[8:9], v[8:9], v[10:11]
	v_mov_b32_e32 v6, v77
	v_mov_b32_e32 v7, v81
	v_mov_b32_e32 v12, v84
	v_mov_b32_e32 v13, v88
	v_pk_fma_f32 v[10:11], v[16:17], v[16:17], v[18:19]
	v_pk_fma_f32 v[4:5], v[4:5], v[4:5], v[8:9]
	v_mov_b32_e32 v14, v85
	v_mov_b32_e32 v15, v89
	v_pk_fma_f32 v[8:9], v[12:13], v[12:13], v[10:11]
	v_pk_fma_f32 v[4:5], v[6:7], v[6:7], v[4:5]
	v_pk_fma_f32 v[6:7], v[14:15], v[14:15], v[8:9]
	v_add_f32_e32 v3, v4, v5
	v_add_f32_e32 v3, v3, v6
	v_add_f32_e32 v3, v3, v7
	ds_bpermute_b32 v5, v68, v3
	v_cndmask_b32_e64 v4, v48, v66, s[2:3]
	v_cndmask_b32_e32 v6, v48, v64, vcc
	v_addc_co_u32_e64 v95, s[6:7], 0, v1, s[6:7]
	s_waitcnt lgkmcnt(0)
	v_add_f32_e32 v5, v3, v5
	ds_bpermute_b32 v7, v69, v5
	v_ashrrev_i32_e32 v3, 31, v2
	v_lshlrev_b64 v[0:1], 12, v[2:3]
	v_lshl_add_u64 v[0:1], v[54:55], 0, v[0:1]
	global_load_dwordx4 v[44:47], v[0:1], off
	global_load_dwordx4 v[40:43], v[0:1], off offset:1024
	global_load_dwordx4 v[36:39], v[0:1], off offset:2048
	global_load_dwordx4 v[32:35], v[0:1], off offset:3072
	s_waitcnt lgkmcnt(0)
	v_add_f32_e32 v8, v5, v7
	ds_bpermute_b32 v9, v70, v8
	v_ashrrev_i32_e32 v5, 31, v4
	v_ashrrev_i32_e32 v7, 31, v6
	v_lshlrev_b64 v[2:3], 12, v[4:5]
	v_lshlrev_b64 v[4:5], 12, v[6:7]
	s_waitcnt lgkmcnt(0)
	v_add_f32_e32 v8, v8, v9
	ds_bpermute_b32 v9, v71, v8
	v_lshl_add_u64 v[96:97], v[54:55], 0, v[4:5]
	v_lshl_add_u64 v[2:3], v[54:55], 0, v[2:3]
	global_load_dwordx4 v[28:31], v[2:3], off
	global_load_dwordx4 v[24:27], v[2:3], off offset:1024
	global_load_dwordx4 v[20:23], v[2:3], off offset:2048
	global_load_dwordx4 v[16:19], v[2:3], off offset:3072
	s_waitcnt lgkmcnt(0)
	v_add_f32_e32 v4, v8, v9
	ds_bpermute_b32 v5, v72, v4
	s_waitcnt lgkmcnt(0)
	v_add_f32_e32 v0, v4, v5
	ds_bpermute_b32 v1, v73, v0
	s_waitcnt lgkmcnt(0)
	v_add_f32_e32 v0, v0, v1
	v_fmamk_f32 v0, v0, 0x3a800000, v49
	v_mul_f32_e32 v1, 0x4b800000, v0
	v_cmp_gt_f32_e64 s[6:7], s13, v0
	s_waitcnt vmcnt(4)
	v_pk_mul_f32 v[98:99], v[32:33], v[32:33]
	v_cndmask_b32_e64 v0, v0, v1, s[6:7]
	v_rsq_f32_e32 v65, v0
	global_load_dwordx4 v[12:15], v[96:97], off
	global_load_dwordx4 v[8:11], v[96:97], off offset:1024
	global_load_dwordx4 v[4:7], v[96:97], off offset:2048
	global_load_dwordx4 v[0:3], v[96:97], off offset:3072
	v_pk_mul_f32 v[100:101], v[34:35], v[34:35]
	v_mul_f32_e32 v67, 0x45800000, v65
	v_cndmask_b32_e64 v96, v65, v67, s[6:7]
	v_pk_mul_f32 v[74:75], v[74:75], v[96:97] op_sel_hi:[1,0]
	v_pk_mul_f32 v[76:77], v[76:77], v[96:97] op_sel_hi:[1,0]
	v_pk_mul_f32 v[74:75], v[104:105], v[74:75]
	v_pk_mul_f32 v[76:77], v[106:107], v[76:77]
	v_cvt_pk_bf16_f32 v74, v74, v75
	v_cvt_pk_bf16_f32 v75, v76, v77
	global_store_dwordx2 v[94:95], v[74:75], off
	v_pk_mul_f32 v[78:79], v[78:79], v[96:97] op_sel_hi:[1,0]
	v_pk_mul_f32 v[80:81], v[80:81], v[96:97] op_sel_hi:[1,0]
	v_pk_mul_f32 v[90:91], v[36:37], v[36:37]
	v_pk_mul_f32 v[92:93], v[38:39], v[38:39]
	s_waitcnt vmcnt(0)
	v_pk_mul_f32 v[74:75], v[108:109], v[78:79]
	v_pk_mul_f32 v[76:77], v[110:111], v[80:81]
	v_cvt_pk_bf16_f32 v74, v74, v75
	v_cvt_pk_bf16_f32 v75, v76, v77
	global_store_dwordx2 v[94:95], v[74:75], off offset:512
	v_pk_mul_f32 v[78:79], v[82:83], v[96:97] op_sel_hi:[1,0]
	v_pk_mul_f32 v[80:81], v[84:85], v[96:97] op_sel_hi:[1,0]
	v_pk_mul_f32 v[82:83], v[40:41], v[40:41]
	v_pk_mul_f32 v[84:85], v[42:43], v[42:43]
	v_add_f32_e32 v65, v82, v83
	v_add_f32_e32 v65, v65, v84
	v_add_f32_e32 v65, v65, v85
	v_pk_mul_f32 v[74:75], v[78:79], v[112:113]
	v_pk_mul_f32 v[76:77], v[80:81], v[114:115]
	v_cvt_pk_bf16_f32 v74, v74, v75
	v_cvt_pk_bf16_f32 v75, v76, v77
	global_store_dwordx2 v[94:95], v[74:75], off offset:1024
	v_pk_mul_f32 v[78:79], v[44:45], v[44:45]
	v_pk_mul_f32 v[80:81], v[46:47], v[46:47]
	v_add_f32_e32 v67, v78, v79
	v_add_f32_e32 v78, v90, v91
	v_add_f32_e32 v67, v67, v80
	v_add_f32_e32 v79, v98, v99
	v_add_f32_e32 v78, v78, v92
	v_add_f32_e32 v67, v67, v81
	v_add_f32_e32 v79, v79, v100
	v_add_f32_e32 v78, v78, v93
	v_add_f32_e32 v65, v67, v65
	v_add_f32_e32 v79, v79, v101
	v_add_f32_e32 v65, v65, v78
	v_add_f32_e32 v65, v65, v79
	ds_bpermute_b32 v67, v68, v65
	v_pk_mul_f32 v[78:79], v[86:87], v[96:97] op_sel_hi:[1,0]
	v_pk_mul_f32 v[80:81], v[88:89], v[96:97] op_sel_hi:[1,0]
	s_waitcnt lgkmcnt(0)
	v_add_f32_e32 v65, v65, v67
	ds_bpermute_b32 v67, v69, v65
	s_waitcnt lgkmcnt(0)
	v_add_f32_e32 v65, v65, v67
	ds_bpermute_b32 v67, v70, v65
	s_waitcnt lgkmcnt(0)
	v_add_f32_e32 v65, v65, v67
	ds_bpermute_b32 v67, v71, v65
	s_waitcnt lgkmcnt(0)
	v_add_f32_e32 v65, v65, v67
	ds_bpermute_b32 v67, v72, v65
	s_waitcnt lgkmcnt(0)
	v_add_f32_e32 v65, v65, v67
	ds_bpermute_b32 v67, v73, v65
	v_pk_mul_f32 v[74:75], v[78:79], v[116:117]
	v_pk_mul_f32 v[76:77], v[80:81], v[118:119]
	v_cvt_pk_bf16_f32 v74, v74, v75
	v_cvt_pk_bf16_f32 v75, v76, v77
	global_store_dwordx2 v[94:95], v[74:75], off offset:1536
	s_and_saveexec_b64 s[20:21], s[4:5]
	s_cbranch_execz .LBB0_338
; DEVI void phase_norm2(const Params& p) {
;     ...
; #pragma unroll
;     for (int u = 0; u < 4; ++u) {
;       const int o = o0 + u * stride;
;       float ss = 0.f;
; #pragma unroll
;       for (int j = 0; j < 4; ++j) ss += v[u][j].x * v[u][j].x + v[u][j].y * v[u][j].y + v[u][j].z * v[u][j].z + v[u][j].w * v[u][j].w;
;       ss = wsum(ss);
;       float rs = rsqrtf(ss * (1.f / 1024.f) + EPSN);
;       if (o < OROWS) {
; #pragma unroll
;         for (int j = 0; j < 4; ++j) {
;           float4 w = *(const float4*)(p.norm2_w + (j * 64 + lane) * 4);
;           uint2 ov;
;           ov.x = pk2(v[u][j].x * rs * w.x, v[u][j].y * rs * w.y);
;           ov.y = pk2(v[u][j].z * rs * w.z, v[u][j].w * rs * w.w);
;           *(uint2*)(P_U2 + (size_t)o * 1024 + (j * 64 + lane) * 4) = ov;
;         }
;       }
	s_waitcnt lgkmcnt(0)
	v_add_f32_e32 v65, v65, v67
	v_fmamk_f32 v65, v65, 0x3a800000, v49
	v_mul_f32_e32 v67, 0x4b800000, v65
	v_cmp_gt_f32_e64 s[4:5], s13, v65
	v_lshl_add_u64 v[78:79], v[58:59], 0, v[50:51]
	v_add_co_u32_e64 v78, s[6:7], s23, v78
	v_cndmask_b32_e64 v65, v65, v67, s[4:5]
	v_rsq_f32_e32 v65, v65
	v_addc_co_u32_e64 v79, s[6:7], 0, v79, s[6:7]
	v_mul_f32_e32 v67, 0x45800000, v65
	v_cndmask_b32_e64 v80, v65, v67, s[4:5]
	v_pk_mul_f32 v[44:45], v[44:45], v[80:81] op_sel_hi:[1,0]
	v_pk_mul_f32 v[46:47], v[46:47], v[80:81] op_sel_hi:[1,0]
	v_pk_mul_f32 v[40:41], v[40:41], v[80:81] op_sel_hi:[1,0]
	v_pk_mul_f32 v[42:43], v[42:43], v[80:81] op_sel_hi:[1,0]
	v_pk_mul_f32 v[36:37], v[36:37], v[80:81] op_sel_hi:[1,0]
	v_pk_mul_f32 v[38:39], v[38:39], v[80:81] op_sel_hi:[1,0]
	v_pk_mul_f32 v[32:33], v[32:33], v[80:81] op_sel_hi:[1,0]
	v_pk_mul_f32 v[34:35], v[34:35], v[80:81] op_sel_hi:[1,0]
	v_pk_mul_f32 v[44:45], v[44:45], v[104:105]
	v_pk_mul_f32 v[46:47], v[46:47], v[106:107]
	v_cvt_pk_bf16_f32 v44, v44, v45
	v_cvt_pk_bf16_f32 v45, v46, v47
	global_store_dwordx2 v[78:79], v[44:45], off
	v_pk_mul_f32 v[40:41], v[40:41], v[108:109]
	v_pk_mul_f32 v[42:43], v[42:43], v[110:111]
	v_cvt_pk_bf16_f32 v40, v40, v41
	v_cvt_pk_bf16_f32 v41, v42, v43
	global_store_dwordx2 v[78:79], v[40:41], off offset:512
	v_pk_mul_f32 v[36:37], v[36:37], v[112:113]
	v_pk_mul_f32 v[38:39], v[38:39], v[114:115]
	v_cvt_pk_bf16_f32 v36, v36, v37
	v_cvt_pk_bf16_f32 v37, v38, v39
	global_store_dwordx2 v[78:79], v[36:37], off offset:1024
	v_pk_mul_f32 v[32:33], v[32:33], v[116:117]
	v_pk_mul_f32 v[34:35], v[34:35], v[118:119]
	v_cvt_pk_bf16_f32 v32, v32, v33
	v_cvt_pk_bf16_f32 v33, v34, v35
	global_store_dwordx2 v[78:79], v[32:33], off offset:1536
.LBB0_338:
	s_or_b64 exec, exec, s[20:21]
	v_pk_mul_f32 v[32:33], v[28:29], v[28:29]
	v_pk_mul_f32 v[36:37], v[24:25], v[24:25]
	v_pk_mul_f32 v[34:35], v[30:31], v[30:31]
	v_pk_mul_f32 v[38:39], v[26:27], v[26:27]
	v_pk_mul_f32 v[40:41], v[20:21], v[20:21]
	v_add_f32_e32 v36, v36, v37
	v_add_f32_e32 v32, v32, v33
	v_pk_mul_f32 v[42:43], v[22:23], v[22:23]
	v_add_f32_e32 v36, v36, v38
	v_add_f32_e32 v32, v32, v34
	v_add_f32_e32 v33, v40, v41
	v_add_f32_e32 v36, v36, v39
	v_add_f32_e32 v32, v32, v35
	v_add_f32_e32 v33, v33, v42
	v_pk_mul_f32 v[44:45], v[16:17], v[16:17]
	v_add_f32_e32 v32, v32, v36
	v_add_f32_e32 v33, v33, v43
	v_pk_mul_f32 v[46:47], v[18:19], v[18:19]
	v_add_f32_e32 v32, v32, v33
	v_add_f32_e32 v33, v44, v45
	v_add_f32_e32 v33, v33, v46
	v_add_f32_e32 v33, v33, v47
	v_add_f32_e32 v32, v32, v33
	ds_bpermute_b32 v33, v68, v32
	s_waitcnt lgkmcnt(0)
	v_add_f32_e32 v32, v32, v33
	ds_bpermute_b32 v33, v69, v32
	s_waitcnt lgkmcnt(0)
	v_add_f32_e32 v32, v32, v33
	ds_bpermute_b32 v33, v70, v32
	s_waitcnt lgkmcnt(0)
	v_add_f32_e32 v32, v32, v33
	ds_bpermute_b32 v33, v71, v32
	s_waitcnt lgkmcnt(0)
	v_add_f32_e32 v32, v32, v33
	ds_bpermute_b32 v33, v72, v32
	s_waitcnt lgkmcnt(0)
	v_add_f32_e32 v32, v32, v33
	ds_bpermute_b32 v33, v73, v32
	s_and_saveexec_b64 s[4:5], s[2:3]
	s_cbranch_execz .LBB0_340
	s_waitcnt lgkmcnt(0)
	v_add_f32_e32 v32, v32, v33
	v_fmamk_f32 v32, v32, 0x3a800000, v49
	v_mul_f32_e32 v33, 0x4b800000, v32
	v_cmp_gt_f32_e64 s[2:3], s13, v32
	v_ashrrev_i32_e32 v67, 31, v66
	s_nop 0
	v_cndmask_b32_e64 v32, v32, v33, s[2:3]
	v_rsq_f32_e32 v38, v32
	v_lshlrev_b64 v[32:33], 11, v[66:67]
	v_lshl_add_u64 v[32:33], v[56:57], 0, v[32:33]
	v_mul_f32_e32 v39, 0x45800000, v38
	v_cndmask_b32_e64 v38, v38, v39, s[2:3]
	v_pk_mul_f32 v[28:29], v[28:29], v[38:39] op_sel_hi:[1,0]
	v_pk_mul_f32 v[30:31], v[30:31], v[38:39] op_sel_hi:[1,0]
	v_pk_mul_f32 v[24:25], v[24:25], v[38:39] op_sel_hi:[1,0]
	v_pk_mul_f32 v[26:27], v[26:27], v[38:39] op_sel_hi:[1,0]
	v_pk_mul_f32 v[20:21], v[20:21], v[38:39] op_sel_hi:[1,0]
	v_pk_mul_f32 v[22:23], v[22:23], v[38:39] op_sel_hi:[1,0]
	v_pk_mul_f32 v[16:17], v[16:17], v[38:39] op_sel_hi:[1,0]
	v_pk_mul_f32 v[18:19], v[18:19], v[38:39] op_sel_hi:[1,0]
	v_pk_mul_f32 v[28:29], v[28:29], v[104:105]
	v_pk_mul_f32 v[30:31], v[30:31], v[106:107]
	v_cvt_pk_bf16_f32 v28, v28, v29
	v_cvt_pk_bf16_f32 v29, v30, v31
	global_store_dwordx2 v[32:33], v[28:29], off
	v_pk_mul_f32 v[24:25], v[24:25], v[108:109]
	v_pk_mul_f32 v[26:27], v[26:27], v[110:111]
	v_cvt_pk_bf16_f32 v24, v24, v25
	v_cvt_pk_bf16_f32 v25, v26, v27
	global_store_dwordx2 v[32:33], v[24:25], off offset:512
	v_pk_mul_f32 v[20:21], v[20:21], v[112:113]
	v_pk_mul_f32 v[22:23], v[22:23], v[114:115]
	v_cvt_pk_bf16_f32 v20, v20, v21
	v_cvt_pk_bf16_f32 v21, v22, v23
	global_store_dwordx2 v[32:33], v[20:21], off offset:1024
	v_pk_mul_f32 v[16:17], v[16:17], v[116:117]
	v_pk_mul_f32 v[18:19], v[18:19], v[118:119]
	v_cvt_pk_bf16_f32 v16, v16, v17
	v_cvt_pk_bf16_f32 v17, v18, v19
	global_store_dwordx2 v[32:33], v[16:17], off offset:1536
; DEVI void phase_norm2(const Params& p) {
;     ...
; #pragma unroll
;     for (int u = 0; u < 4; ++u) {
;       const int o = o0 + u * stride;
;       float ss = 0.f;
; #pragma unroll
;       for (int j = 0; j < 4; ++j) ss += v[u][j].x * v[u][j].x + v[u][j].y * v[u][j].y + v[u][j].z * v[u][j].z + v[u][j].w * v[u][j].w;
;       ss = wsum(ss);
;       float rs = rsqrtf(ss * (1.f / 1024.f) + EPSN);
;       if (o < OROWS) {
; #pragma unroll
;         for (int j = 0; j < 4; ++j) {
;           float4 w = *(const float4*)(p.norm2_w + (j * 64 + lane) * 4);
;           uint2 ov;
;           ov.x = pk2(v[u][j].x * rs * w.x, v[u][j].y * rs * w.y);
;           ov.y = pk2(v[u][j].z * rs * w.z, v[u][j].w * rs * w.w);
;           *(uint2*)(P_U2 + (size_t)o * 1024 + (j * 64 + lane) * 4) = ov;
;         }
;       }
.LBB0_340:
	s_or_b64 exec, exec, s[4:5]
	v_pk_mul_f32 v[16:17], v[12:13], v[12:13]
	v_pk_mul_f32 v[20:21], v[8:9], v[8:9]
	v_pk_mul_f32 v[18:19], v[14:15], v[14:15]
	v_pk_mul_f32 v[22:23], v[10:11], v[10:11]
	v_pk_mul_f32 v[24:25], v[4:5], v[4:5]
	v_add_f32_e32 v20, v20, v21
	v_add_f32_e32 v16, v16, v17
	v_pk_mul_f32 v[26:27], v[6:7], v[6:7]
	v_add_f32_e32 v20, v20, v22
	v_add_f32_e32 v16, v16, v18
	v_add_f32_e32 v17, v24, v25
	v_add_f32_e32 v20, v20, v23
	v_add_f32_e32 v16, v16, v19
	v_add_f32_e32 v17, v17, v26
	v_pk_mul_f32 v[28:29], v[0:1], v[0:1]
	v_add_f32_e32 v16, v16, v20
	v_add_f32_e32 v17, v17, v27
	v_pk_mul_f32 v[30:31], v[2:3], v[2:3]
	v_add_f32_e32 v16, v16, v17
	v_add_f32_e32 v17, v28, v29
	v_add_f32_e32 v17, v17, v30
	v_add_f32_e32 v17, v17, v31
	v_add_f32_e32 v16, v16, v17
	ds_bpermute_b32 v17, v68, v16
	s_waitcnt lgkmcnt(0)
	v_add_f32_e32 v16, v16, v17
	ds_bpermute_b32 v17, v69, v16
	s_waitcnt lgkmcnt(0)
	v_add_f32_e32 v16, v16, v17
	ds_bpermute_b32 v17, v70, v16
	s_waitcnt lgkmcnt(0)
	v_add_f32_e32 v16, v16, v17
	ds_bpermute_b32 v17, v71, v16
	s_waitcnt lgkmcnt(0)
	v_add_f32_e32 v16, v16, v17
	ds_bpermute_b32 v17, v72, v16
	s_waitcnt lgkmcnt(0)
	v_add_f32_e32 v16, v16, v17
	ds_bpermute_b32 v17, v73, v16
	s_and_saveexec_b64 s[2:3], vcc
	s_cbranch_execz .LBB0_335
	s_waitcnt lgkmcnt(0)
	v_add_f32_e32 v16, v16, v17
	v_fmamk_f32 v16, v16, 0x3a800000, v49
	v_mul_f32_e32 v17, 0x4b800000, v16
	v_cmp_gt_f32_e32 vcc, s13, v16
	v_ashrrev_i32_e32 v65, 31, v64
	s_nop 0
	v_cndmask_b32_e32 v16, v16, v17, vcc
	v_rsq_f32_e32 v22, v16
	v_lshlrev_b64 v[16:17], 11, v[64:65]
	v_lshl_add_u64 v[16:17], v[56:57], 0, v[16:17]
	v_mul_f32_e32 v23, 0x45800000, v22
	v_cndmask_b32_e32 v22, v22, v23, vcc
	v_pk_mul_f32 v[12:13], v[12:13], v[22:23] op_sel_hi:[1,0]
	v_pk_mul_f32 v[14:15], v[14:15], v[22:23] op_sel_hi:[1,0]
	v_pk_mul_f32 v[8:9], v[8:9], v[22:23] op_sel_hi:[1,0]
	v_pk_mul_f32 v[10:11], v[10:11], v[22:23] op_sel_hi:[1,0]
	v_pk_mul_f32 v[4:5], v[4:5], v[22:23] op_sel_hi:[1,0]
	v_pk_mul_f32 v[6:7], v[6:7], v[22:23] op_sel_hi:[1,0]
	v_pk_mul_f32 v[0:1], v[0:1], v[22:23] op_sel_hi:[1,0]
	v_pk_mul_f32 v[2:3], v[2:3], v[22:23] op_sel_hi:[1,0]
	v_pk_mul_f32 v[12:13], v[12:13], v[104:105]
	v_pk_mul_f32 v[14:15], v[14:15], v[106:107]
	v_cvt_pk_bf16_f32 v12, v12, v13
	v_cvt_pk_bf16_f32 v13, v14, v15
	global_store_dwordx2 v[16:17], v[12:13], off
	v_pk_mul_f32 v[8:9], v[8:9], v[108:109]
	v_pk_mul_f32 v[10:11], v[10:11], v[110:111]
	v_cvt_pk_bf16_f32 v8, v8, v9
	v_cvt_pk_bf16_f32 v9, v10, v11
	global_store_dwordx2 v[16:17], v[8:9], off offset:512
	v_pk_mul_f32 v[4:5], v[4:5], v[112:113]
	v_pk_mul_f32 v[6:7], v[6:7], v[114:115]
	v_cvt_pk_bf16_f32 v4, v4, v5
	v_cvt_pk_bf16_f32 v5, v6, v7
	global_store_dwordx2 v[16:17], v[4:5], off offset:1024
	v_pk_mul_f32 v[0:1], v[0:1], v[116:117]
	v_pk_mul_f32 v[2:3], v[2:3], v[118:119]
	v_cvt_pk_bf16_f32 v0, v0, v1
	v_cvt_pk_bf16_f32 v1, v2, v3
	global_store_dwordx2 v[16:17], v[0:1], off offset:1536
	s_branch .LBB0_335

; DEVI void phase_final(const Params& p) {
;   int tid0_ = threadIdx.x;
;   asm volatile("" : "+v"(tid0_));
;   const int lane = tid0_ & 63, wid = tid0_ >> 6;
;   const int stride = gridDim.x * 8;
;   for (int o0 = blockIdx.x * 8 + wid; o0 < OROWS; o0 += stride * 4) {
;     float4 v[4][4];
; #pragma unroll
;     for (int u = 0; u < 4; ++u) {
;       const int o = (o0 + u * stride < OROWS) ? o0 + u * stride : o0;
;       const float* src = p.out + (size_t)o * 1024;
; #pragma unroll
;       for (int j = 0; j < 4; ++j) v[u][j] = *(const float4*)(src + (j * 64 + lane) * 4);
.LBB0_398:
	s_or_b64 exec, exec, s[0:1]
	s_barrier
	s_mov_b32 s12, 0x14000
	v_ashrrev_i32_e32 v0, 6, v164
	v_add_u32_e32 v48, s65, v0
	v_cmp_gt_i32_e32 vcc, s12, v48
	s_and_saveexec_b64 s[0:1], vcc
	s_cbranch_execz .LBB0_407
	v_xor_b32_e32 v0, 32, v165
	v_cmp_lt_i32_e32 vcc, v0, v166
	v_mov_b32_e32 v51, 0
	v_ashrrev_i32_e32 v49, 31, v48
	v_cndmask_b32_e32 v0, v165, v0, vcc
	v_lshlrev_b32_e32 v66, 2, v0
	v_xor_b32_e32 v0, 16, v165
	v_cmp_lt_i32_e32 vcc, v0, v166
	s_lshl_b32 s6, s64, 5
	s_ashr_i32 s7, s6, 31
	v_cndmask_b32_e32 v0, v165, v0, vcc
	v_lshlrev_b32_e32 v67, 2, v0
	v_xor_b32_e32 v0, 8, v165
	v_cmp_lt_i32_e32 vcc, v0, v166
	s_lshl_b32 s13, s64, 4
	s_lshl_b64 s[8:9], s[6:7], 12
	v_cndmask_b32_e32 v0, v165, v0, vcc
	v_lshlrev_b32_e32 v68, 2, v0
	v_xor_b32_e32 v0, 4, v165
	v_cmp_lt_i32_e32 vcc, v0, v166
	s_mov_b64 s[10:11], 0
	s_mov_b32 s7, 0x800000
	v_cndmask_b32_e32 v0, v165, v0, vcc
	v_lshlrev_b32_e32 v69, 2, v0
	v_xor_b32_e32 v0, 2, v165
	v_cmp_lt_i32_e32 vcc, v0, v166
	s_mov_b32 s14, 0x13fff
	s_nop 0
	v_cndmask_b32_e32 v0, v165, v0, vcc
	v_lshlrev_b32_e32 v70, 2, v0
	v_xor_b32_e32 v0, 1, v165
	v_cmp_lt_i32_e32 vcc, v0, v166
	s_nop 1
	v_cndmask_b32_e32 v0, v165, v0, vcc
	v_lshlrev_b32_e32 v71, 2, v0
	v_lshlrev_b32_e32 v0, 4, v164
	v_and_b32_e32 v50, 0x3f0, v0
	v_and_b32_e32 v0, 63, v164
	v_lshl_add_u64 v[52:53], s[60:61], 0, v[50:51]
	v_lshl_add_u64 v[54:55], s[62:63], 0, v[50:51]
	v_lshlrev_b32_e32 v50, 4, v0
	v_lshlrev_b64 v[0:1], 12, v[48:49]
	v_lshl_add_u64 v[56:57], s[62:63], 0, v[0:1]
	v_add_u32_e32 v0, s38, v48
	v_ashrrev_i32_e32 v1, 31, v0
	v_lshlrev_b64 v[0:1], 12, v[0:1]
	v_lshl_add_u64 v[58:59], s[62:63], 0, v[0:1]
	v_mov_b32_e32 v49, 0x3727c5ac
	global_load_dwordx4 v[100:103], v[52:53], off
	global_load_dwordx4 v[104:107], v[52:53], off offset:1024
	global_load_dwordx4 v[108:111], v[52:53], off offset:2048
	global_load_dwordx4 v[112:115], v[52:53], off offset:3072
	s_branch .LBB0_401

; DEVI void phase_final(const Params& p) {
;     ...
;   for (int o0 = blockIdx.x * 8 + wid; o0 < OROWS; o0 += stride * 4) {
;     float4 v[4][4];
; #pragma unroll
;     for (int u = 0; u < 4; ++u) {
;       const int o = (o0 + u * stride < OROWS) ? o0 + u * stride : o0;
;       const float* src = p.out + (size_t)o * 1024;
; #pragma unroll
;       for (int j = 0; j < 4; ++j) v[u][j] = *(const float4*)(src + (j * 64 + lane) * 4);
;     }
; #pragma unroll
;     for (int u = 0; u < 4; ++u) {
;       const int o = o0 + u * stride;
;       float ss = 0.f;
; #pragma unroll
;       for (int j = 0; j < 4; ++j) ss += v[u][j].x * v[u][j].x + v[u][j].y * v[u][j].y + v[u][j].z * v[u][j].z + v[u][j].w * v[u][j].w;
;       ss = wsum(ss);
;       float rs = rsqrtf(ss * (1.f / 1024.f) + EPSN);
;       if (o < OROWS) {
;         float* dst = p.out + (size_t)o * 1024;
; #pragma unroll
;         for (int j = 0; j < 4; ++j) {
;           float4 w = *(const float4*)(p.final_norm_w + (j * 64 + lane) * 4);
;           float4 ov;
;           ov.x = v[u][j].x * rs * w.x; ov.y = v[u][j].y * rs * w.y; ov.z = v[u][j].z * rs * w.z; ov.w = v[u][j].w * rs * w.w;
;           *(float4*)(dst + (j * 64 + lane) * 4) = ov;
;         }
;       }
.LBB0_401:
	v_lshl_add_u64 v[64:65], v[56:57], 0, v[50:51]
	global_load_dwordx4 v[72:75], v[64:65], off
	global_load_dwordx4 v[76:79], v[64:65], off offset:1024
	global_load_dwordx4 v[80:83], v[64:65], off offset:2048
	global_load_dwordx4 v[84:87], v[64:65], off offset:3072
	v_add_u32_e32 v60, s39, v48
	v_cmp_gt_i32_e32 vcc, s12, v60
	v_add_u32_e32 v16, s38, v48
	v_cmp_gt_i32_e64 s[2:3], s12, v16
	v_add_u32_e32 v62, s13, v48
	v_cmp_gt_i32_e64 s[0:1], s12, v62
	s_waitcnt vmcnt(3)
	v_mov_b32_e32 v2, v73
	s_waitcnt vmcnt(2)
	v_mov_b32_e32 v3, v77
	v_mov_b32_e32 v0, v72
	v_mov_b32_e32 v1, v76
	s_waitcnt vmcnt(1)
	v_mov_b32_e32 v10, v81
	s_waitcnt vmcnt(0)
	v_mov_b32_e32 v11, v85
	v_pk_mul_f32 v[2:3], v[2:3], v[2:3]
	v_mov_b32_e32 v4, v74
	v_mov_b32_e32 v5, v78
	v_mov_b32_e32 v8, v80
	v_mov_b32_e32 v9, v84
	v_pk_mul_f32 v[10:11], v[10:11], v[10:11]
	v_pk_fma_f32 v[0:1], v[0:1], v[0:1], v[2:3]
	v_mov_b32_e32 v6, v75
	v_mov_b32_e32 v7, v79
	v_mov_b32_e32 v12, v82
	v_mov_b32_e32 v13, v86
	v_pk_fma_f32 v[2:3], v[8:9], v[8:9], v[10:11]
	v_pk_fma_f32 v[0:1], v[4:5], v[4:5], v[0:1]
	v_mov_b32_e32 v14, v83
	v_mov_b32_e32 v15, v87
	v_pk_fma_f32 v[2:3], v[12:13], v[12:13], v[2:3]
	v_pk_fma_f32 v[0:1], v[6:7], v[6:7], v[0:1]
	v_pk_fma_f32 v[2:3], v[14:15], v[14:15], v[2:3]
	v_add_f32_e32 v0, v0, v1
	v_add_f32_e32 v0, v0, v2
	v_add_f32_e32 v1, v0, v3
	ds_bpermute_b32 v2, v66, v1
	v_cndmask_b32_e32 v4, v48, v60, vcc
	v_cndmask_b32_e64 v0, v48, v16, s[2:3]
	s_waitcnt lgkmcnt(0)
	v_add_f32_e32 v3, v1, v2
	ds_bpermute_b32 v5, v67, v3
	v_ashrrev_i32_e32 v1, 31, v0
	v_lshlrev_b64 v[0:1], 12, v[0:1]
	v_lshl_add_u64 v[0:1], v[54:55], 0, v[0:1]
	global_load_dwordx4 v[44:47], v[0:1], off
	global_load_dwordx4 v[40:43], v[0:1], off offset:1024
	global_load_dwordx4 v[36:39], v[0:1], off offset:2048
	global_load_dwordx4 v[32:35], v[0:1], off offset:3072
	s_waitcnt lgkmcnt(0)
	v_add_f32_e32 v6, v3, v5
	ds_bpermute_b32 v7, v68, v6
	v_ashrrev_i32_e32 v5, 31, v4
	v_lshlrev_b64 v[4:5], 12, v[4:5]
	v_lshl_add_u64 v[92:93], v[54:55], 0, v[4:5]
	v_cndmask_b32_e64 v2, v48, v62, s[0:1]
	s_waitcnt lgkmcnt(0)
	v_add_f32_e32 v6, v6, v7
	ds_bpermute_b32 v7, v69, v6
	v_ashrrev_i32_e32 v3, 31, v2
	v_lshlrev_b64 v[2:3], 12, v[2:3]
	v_lshl_add_u64 v[2:3], v[54:55], 0, v[2:3]
	global_load_dwordx4 v[28:31], v[2:3], off
	global_load_dwordx4 v[24:27], v[2:3], off offset:1024
	global_load_dwordx4 v[20:23], v[2:3], off offset:2048
	global_load_dwordx4 v[16:19], v[2:3], off offset:3072
	s_waitcnt lgkmcnt(0)
	v_add_f32_e32 v4, v6, v7
	ds_bpermute_b32 v5, v70, v4
	s_waitcnt lgkmcnt(0)
	v_add_f32_e32 v0, v4, v5
	ds_bpermute_b32 v1, v71, v0
	s_waitcnt lgkmcnt(0)
	v_add_f32_e32 v0, v0, v1
	v_fmamk_f32 v0, v0, 0x3a800000, v49
	v_mul_f32_e32 v1, 0x4b800000, v0
	v_cmp_gt_f32_e64 s[4:5], s7, v0
	s_waitcnt vmcnt(4)
	v_pk_mul_f32 v[94:95], v[32:33], v[32:33]
	v_cndmask_b32_e64 v0, v0, v1, s[4:5]
	v_rsq_f32_e32 v61, v0
	global_load_dwordx4 v[12:15], v[92:93], off
	global_load_dwordx4 v[8:11], v[92:93], off offset:1024
	global_load_dwordx4 v[4:7], v[92:93], off offset:2048
	global_load_dwordx4 v[0:3], v[92:93], off offset:3072
	v_pk_mul_f32 v[96:97], v[34:35], v[34:35]
	v_mul_f32_e32 v63, 0x45800000, v61
	v_cndmask_b32_e64 v92, v61, v63, s[4:5]
	v_pk_mul_f32 v[72:73], v[72:73], v[92:93] op_sel_hi:[1,0]
	v_pk_mul_f32 v[74:75], v[74:75], v[92:93] op_sel_hi:[1,0]
	v_pk_mul_f32 v[72:73], v[100:101], v[72:73]
	v_pk_mul_f32 v[74:75], v[102:103], v[74:75]
	global_store_dwordx4 v[64:65], v[72:75], off
	v_pk_mul_f32 v[76:77], v[76:77], v[92:93] op_sel_hi:[1,0]
	v_pk_mul_f32 v[78:79], v[78:79], v[92:93] op_sel_hi:[1,0]
	v_pk_mul_f32 v[88:89], v[36:37], v[36:37]
	v_pk_mul_f32 v[90:91], v[38:39], v[38:39]
	s_waitcnt vmcnt(0)
	v_pk_mul_f32 v[72:73], v[104:105], v[76:77]
	v_pk_mul_f32 v[74:75], v[78:79], v[106:107]
	global_store_dwordx4 v[64:65], v[72:75], off offset:1024
	v_pk_mul_f32 v[76:77], v[80:81], v[92:93] op_sel_hi:[1,0]
	v_pk_mul_f32 v[78:79], v[82:83], v[92:93] op_sel_hi:[1,0]
	v_pk_mul_f32 v[80:81], v[40:41], v[40:41]
	v_pk_mul_f32 v[82:83], v[42:43], v[42:43]
	v_add_f32_e32 v61, v80, v81
	v_add_f32_e32 v61, v61, v82
	v_add_f32_e32 v61, v61, v83
	v_pk_mul_f32 v[72:73], v[76:77], v[108:109]
	v_pk_mul_f32 v[74:75], v[78:79], v[110:111]
	global_store_dwordx4 v[64:65], v[72:75], off offset:2048
	v_pk_mul_f32 v[76:77], v[44:45], v[44:45]
	v_pk_mul_f32 v[78:79], v[46:47], v[46:47]
	v_add_f32_e32 v63, v76, v77
	v_add_f32_e32 v76, v88, v89
	v_add_f32_e32 v63, v63, v78
	v_add_f32_e32 v77, v94, v95
	v_add_f32_e32 v76, v76, v90
	v_add_f32_e32 v63, v63, v79
	v_add_f32_e32 v77, v77, v96
	v_add_f32_e32 v76, v76, v91
	v_add_f32_e32 v61, v63, v61
	v_add_f32_e32 v77, v77, v97
	v_add_f32_e32 v61, v61, v76
	v_add_f32_e32 v61, v61, v77
	ds_bpermute_b32 v63, v66, v61
	v_pk_mul_f32 v[76:77], v[84:85], v[92:93] op_sel_hi:[1,0]
	v_pk_mul_f32 v[78:79], v[86:87], v[92:93] op_sel_hi:[1,0]
	s_waitcnt lgkmcnt(0)
	v_add_f32_e32 v61, v61, v63
	ds_bpermute_b32 v63, v67, v61
	s_waitcnt lgkmcnt(0)
	v_add_f32_e32 v61, v61, v63
	ds_bpermute_b32 v63, v68, v61
	s_waitcnt lgkmcnt(0)
	v_add_f32_e32 v61, v61, v63
	ds_bpermute_b32 v63, v69, v61
	s_waitcnt lgkmcnt(0)
	v_add_f32_e32 v61, v61, v63
	ds_bpermute_b32 v63, v70, v61
	s_waitcnt lgkmcnt(0)
	v_add_f32_e32 v61, v61, v63
	ds_bpermute_b32 v63, v71, v61
	v_pk_mul_f32 v[72:73], v[76:77], v[112:113]
	v_pk_mul_f32 v[74:75], v[78:79], v[114:115]
	global_store_dwordx4 v[64:65], v[72:75], off offset:3072
	s_and_saveexec_b64 s[4:5], s[2:3]
	s_cbranch_execz .LBB0_403
	s_waitcnt lgkmcnt(0)
	v_add_f32_e32 v61, v61, v63
	v_fmamk_f32 v61, v61, 0x3a800000, v49
	v_mul_f32_e32 v63, 0x4b800000, v61
	v_cmp_gt_f32_e64 s[2:3], s7, v61
	v_lshl_add_u64 v[64:65], v[58:59], 0, v[50:51]
	s_nop 0
	v_cndmask_b32_e64 v61, v61, v63, s[2:3]
	v_rsq_f32_e32 v61, v61
	s_nop 0
	v_mul_f32_e32 v63, 0x45800000, v61
	v_cndmask_b32_e64 v76, v61, v63, s[2:3]
	v_pk_mul_f32 v[44:45], v[44:45], v[76:77] op_sel_hi:[1,0]
	v_pk_mul_f32 v[46:47], v[46:47], v[76:77] op_sel_hi:[1,0]
	v_pk_mul_f32 v[40:41], v[40:41], v[76:77] op_sel_hi:[1,0]
	v_pk_mul_f32 v[42:43], v[42:43], v[76:77] op_sel_hi:[1,0]
	v_pk_mul_f32 v[36:37], v[36:37], v[76:77] op_sel_hi:[1,0]
	v_pk_mul_f32 v[38:39], v[38:39], v[76:77] op_sel_hi:[1,0]
	v_pk_mul_f32 v[32:33], v[32:33], v[76:77] op_sel_hi:[1,0]
	v_pk_mul_f32 v[34:35], v[34:35], v[76:77] op_sel_hi:[1,0]
	v_pk_mul_f32 v[44:45], v[44:45], v[100:101]
	v_pk_mul_f32 v[46:47], v[46:47], v[102:103]
	global_store_dwordx4 v[64:65], v[44:47], off
	v_pk_mul_f32 v[40:41], v[40:41], v[104:105]
	v_pk_mul_f32 v[42:43], v[42:43], v[106:107]
	global_store_dwordx4 v[64:65], v[40:43], off offset:1024
	v_pk_mul_f32 v[36:37], v[36:37], v[108:109]
	v_pk_mul_f32 v[38:39], v[38:39], v[110:111]
	global_store_dwordx4 v[64:65], v[36:39], off offset:2048
	v_pk_mul_f32 v[32:33], v[32:33], v[112:113]
	v_pk_mul_f32 v[34:35], v[34:35], v[114:115]
	global_store_dwordx4 v[64:65], v[32:35], off offset:3072
; DEVI void phase_final(const Params& p) {
;     ...
; #pragma unroll
;     for (int u = 0; u < 4; ++u) {
;       const int o = o0 + u * stride;
;       float ss = 0.f;
; #pragma unroll
;       for (int j = 0; j < 4; ++j) ss += v[u][j].x * v[u][j].x + v[u][j].y * v[u][j].y + v[u][j].z * v[u][j].z + v[u][j].w * v[u][j].w;
;       ss = wsum(ss);
;       float rs = rsqrtf(ss * (1.f / 1024.f) + EPSN);
;       if (o < OROWS) {
;         float* dst = p.out + (size_t)o * 1024;
; #pragma unroll
;         for (int j = 0; j < 4; ++j) {
;           float4 w = *(const float4*)(p.final_norm_w + (j * 64 + lane) * 4);
;           float4 ov;
;           ov.x = v[u][j].x * rs * w.x; ov.y = v[u][j].y * rs * w.y; ov.z = v[u][j].z * rs * w.z; ov.w = v[u][j].w * rs * w.w;
;           *(float4*)(dst + (j * 64 + lane) * 4) = ov;
;         }
;       }
.LBB0_403:
	s_or_b64 exec, exec, s[4:5]
	s_nop 0
	v_pk_mul_f32 v[32:33], v[28:29], v[28:29]
	v_pk_mul_f32 v[36:37], v[24:25], v[24:25]
	v_pk_mul_f32 v[34:35], v[30:31], v[30:31]
	v_pk_mul_f32 v[38:39], v[26:27], v[26:27]
	v_pk_mul_f32 v[40:41], v[20:21], v[20:21]
	v_add_f32_e32 v36, v36, v37
	v_add_f32_e32 v32, v32, v33
	v_pk_mul_f32 v[42:43], v[22:23], v[22:23]
	v_add_f32_e32 v36, v36, v38
	v_add_f32_e32 v32, v32, v34
	v_add_f32_e32 v33, v40, v41
	v_add_f32_e32 v36, v36, v39
	v_add_f32_e32 v32, v32, v35
	v_add_f32_e32 v33, v33, v42
	v_pk_mul_f32 v[44:45], v[16:17], v[16:17]
	v_add_f32_e32 v32, v32, v36
	v_add_f32_e32 v33, v33, v43
	v_pk_mul_f32 v[46:47], v[18:19], v[18:19]
	v_add_f32_e32 v32, v32, v33
	v_add_f32_e32 v33, v44, v45
	v_add_f32_e32 v33, v33, v46
	v_add_f32_e32 v33, v33, v47
	v_add_f32_e32 v32, v32, v33
	ds_bpermute_b32 v33, v66, v32
	s_waitcnt lgkmcnt(0)
	v_add_f32_e32 v32, v32, v33
	ds_bpermute_b32 v33, v67, v32
	s_waitcnt lgkmcnt(0)
	v_add_f32_e32 v32, v32, v33
	ds_bpermute_b32 v33, v68, v32
	s_waitcnt lgkmcnt(0)
	v_add_f32_e32 v32, v32, v33
	ds_bpermute_b32 v33, v69, v32
	s_waitcnt lgkmcnt(0)
	v_add_f32_e32 v32, v32, v33
	ds_bpermute_b32 v33, v70, v32
	s_waitcnt lgkmcnt(0)
	v_add_f32_e32 v32, v32, v33
	ds_bpermute_b32 v33, v71, v32
	s_and_saveexec_b64 s[2:3], s[0:1]
	s_cbranch_execz .LBB0_405
	s_waitcnt lgkmcnt(0)
	v_add_f32_e32 v32, v32, v33
	v_fmamk_f32 v32, v32, 0x3a800000, v49
	v_mul_f32_e32 v33, 0x4b800000, v32
	v_cmp_gt_f32_e64 s[0:1], s7, v32
	v_ashrrev_i32_e32 v63, 31, v62
	s_nop 0
	v_cndmask_b32_e64 v32, v32, v33, s[0:1]
	v_rsq_f32_e32 v38, v32
	v_lshlrev_b64 v[32:33], 12, v[62:63]
	v_lshl_add_u64 v[32:33], v[54:55], 0, v[32:33]
	v_mul_f32_e32 v39, 0x45800000, v38
	v_cndmask_b32_e64 v38, v38, v39, s[0:1]
	v_pk_mul_f32 v[28:29], v[28:29], v[38:39] op_sel_hi:[1,0]
	v_pk_mul_f32 v[30:31], v[30:31], v[38:39] op_sel_hi:[1,0]
	v_pk_mul_f32 v[24:25], v[24:25], v[38:39] op_sel_hi:[1,0]
	v_pk_mul_f32 v[26:27], v[26:27], v[38:39] op_sel_hi:[1,0]
	v_pk_mul_f32 v[20:21], v[20:21], v[38:39] op_sel_hi:[1,0]
	v_pk_mul_f32 v[22:23], v[22:23], v[38:39] op_sel_hi:[1,0]
	v_pk_mul_f32 v[16:17], v[16:17], v[38:39] op_sel_hi:[1,0]
	v_pk_mul_f32 v[18:19], v[18:19], v[38:39] op_sel_hi:[1,0]
	v_pk_mul_f32 v[28:29], v[28:29], v[100:101]
	v_pk_mul_f32 v[30:31], v[30:31], v[102:103]
	global_store_dwordx4 v[32:33], v[28:31], off
	v_pk_mul_f32 v[24:25], v[24:25], v[104:105]
	v_pk_mul_f32 v[26:27], v[26:27], v[106:107]
	global_store_dwordx4 v[32:33], v[24:27], off offset:1024
	v_pk_mul_f32 v[20:21], v[20:21], v[108:109]
	v_pk_mul_f32 v[22:23], v[22:23], v[110:111]
	global_store_dwordx4 v[32:33], v[20:23], off offset:2048
	v_pk_mul_f32 v[16:17], v[16:17], v[112:113]
	v_pk_mul_f32 v[18:19], v[18:19], v[114:115]
	global_store_dwordx4 v[32:33], v[16:19], off offset:3072
.LBB0_405:
	s_or_b64 exec, exec, s[2:3]
	s_nop 0
	v_pk_mul_f32 v[16:17], v[12:13], v[12:13]
	v_pk_mul_f32 v[20:21], v[8:9], v[8:9]
	v_pk_mul_f32 v[18:19], v[14:15], v[14:15]
	v_pk_mul_f32 v[22:23], v[10:11], v[10:11]
	v_pk_mul_f32 v[24:25], v[4:5], v[4:5]
	v_add_f32_e32 v20, v20, v21
	v_add_f32_e32 v16, v16, v17
	v_pk_mul_f32 v[26:27], v[6:7], v[6:7]
	v_add_f32_e32 v20, v20, v22
	v_add_f32_e32 v16, v16, v18
	v_add_f32_e32 v17, v24, v25
	v_add_f32_e32 v20, v20, v23
	v_add_f32_e32 v16, v16, v19
	v_add_f32_e32 v17, v17, v26
	v_pk_mul_f32 v[28:29], v[0:1], v[0:1]
	v_add_f32_e32 v16, v16, v20
	v_add_f32_e32 v17, v17, v27
	v_pk_mul_f32 v[30:31], v[2:3], v[2:3]
	v_add_f32_e32 v16, v16, v17
	v_add_f32_e32 v17, v28, v29
	v_add_f32_e32 v17, v17, v30
	v_add_f32_e32 v17, v17, v31
	v_add_f32_e32 v16, v16, v17
	ds_bpermute_b32 v17, v66, v16
	s_waitcnt lgkmcnt(0)
	v_add_f32_e32 v16, v16, v17
	ds_bpermute_b32 v17, v67, v16
	s_waitcnt lgkmcnt(0)
	v_add_f32_e32 v16, v16, v17
	ds_bpermute_b32 v17, v68, v16
	s_waitcnt lgkmcnt(0)
	v_add_f32_e32 v16, v16, v17
	ds_bpermute_b32 v17, v69, v16
	s_waitcnt lgkmcnt(0)
	v_add_f32_e32 v16, v16, v17
	ds_bpermute_b32 v17, v70, v16
	s_waitcnt lgkmcnt(0)
	v_add_f32_e32 v16, v16, v17
	ds_bpermute_b32 v17, v71, v16
	s_and_saveexec_b64 s[0:1], vcc
	s_cbranch_execz .LBB0_400
	s_waitcnt lgkmcnt(0)
	v_add_f32_e32 v16, v16, v17
	v_fmamk_f32 v16, v16, 0x3a800000, v49
	v_mul_f32_e32 v17, 0x4b800000, v16
	v_cmp_gt_f32_e32 vcc, s7, v16
	v_ashrrev_i32_e32 v61, 31, v60
	s_nop 0
	v_cndmask_b32_e32 v16, v16, v17, vcc
	v_rsq_f32_e32 v22, v16
	v_lshlrev_b64 v[16:17], 12, v[60:61]
	v_lshl_add_u64 v[16:17], v[54:55], 0, v[16:17]
	v_mul_f32_e32 v23, 0x45800000, v22
	v_cndmask_b32_e32 v22, v22, v23, vcc
	v_pk_mul_f32 v[12:13], v[12:13], v[22:23] op_sel_hi:[1,0]
	v_pk_mul_f32 v[14:15], v[14:15], v[22:23] op_sel_hi:[1,0]
	v_pk_mul_f32 v[8:9], v[8:9], v[22:23] op_sel_hi:[1,0]
	v_pk_mul_f32 v[10:11], v[10:11], v[22:23] op_sel_hi:[1,0]
	v_pk_mul_f32 v[4:5], v[4:5], v[22:23] op_sel_hi:[1,0]
	v_pk_mul_f32 v[6:7], v[6:7], v[22:23] op_sel_hi:[1,0]
	v_pk_mul_f32 v[0:1], v[0:1], v[22:23] op_sel_hi:[1,0]
	v_pk_mul_f32 v[2:3], v[2:3], v[22:23] op_sel_hi:[1,0]
	v_pk_mul_f32 v[12:13], v[12:13], v[100:101]
	v_pk_mul_f32 v[14:15], v[14:15], v[102:103]
	global_store_dwordx4 v[16:17], v[12:15], off
	v_pk_mul_f32 v[8:9], v[8:9], v[104:105]
	v_pk_mul_f32 v[10:11], v[10:11], v[106:107]
	global_store_dwordx4 v[16:17], v[8:11], off offset:1024
	v_pk_mul_f32 v[4:5], v[4:5], v[108:109]
	v_pk_mul_f32 v[6:7], v[6:7], v[110:111]
	global_store_dwordx4 v[16:17], v[4:7], off offset:2048
	v_pk_mul_f32 v[0:1], v[0:1], v[112:113]
	v_pk_mul_f32 v[2:3], v[2:3], v[114:115]
	global_store_dwordx4 v[16:17], v[0:3], off offset:3072
	s_branch .LBB0_400

; __global__ void __launch_bounds__(512, 2) hymba_fwd(Params p) {
;   __shared__ __attribute__((aligned(16))) char lds[LDS_BYTES];
;   cg::grid_group grid = cg::this_grid();
;   phase_prep(p, lds);
;   grid.sync();
;   phase_inproj(p, lds);
;   grid.sync();
;   phase_conv(p);
;   grid.sync();
;   phase_mix(p, lds);
;   grid.sync();
;   phase_ssmnorm(p);
;   grid.sync();
;   phase_outproj(p, lds);
;   grid.sync();
;   phase_norm2(p);
;   grid.sync();
;   phase_up(p, lds);
;   grid.sync();
;   phase_down(p, lds);
;   grid.sync();
;   phase_final(p);
; }
	.amdhsa_kernel _Z9hymba_fwd6Params
		.amdhsa_group_segment_fixed_size 149760
		.amdhsa_private_segment_fixed_size 0
		.amdhsa_kernarg_size 456
		.amdhsa_user_sgpr_count 2
		.amdhsa_user_sgpr_dispatch_ptr 0
		.amdhsa_user_sgpr_queue_ptr 0
		.amdhsa_user_sgpr_kernarg_segment_ptr 1
		.amdhsa_user_sgpr_dispatch_id 0
		.amdhsa_user_sgpr_kernarg_preload_length 0
		.amdhsa_user_sgpr_kernarg_preload_offset 0
		.amdhsa_user_sgpr_private_segment_size 0
		.amdhsa_uses_dynamic_stack 0
		.amdhsa_enable_private_segment 0
		.amdhsa_system_sgpr_workgroup_id_x 1
		.amdhsa_system_sgpr_workgroup_id_y 0
		.amdhsa_system_sgpr_workgroup_id_z 0
		.amdhsa_system_sgpr_workgroup_info 0
		.amdhsa_system_vgpr_workitem_id 2
		.amdhsa_next_free_vgpr 256
		.amdhsa_next_free_sgpr 102
		.amdhsa_accum_offset 256
		.amdhsa_reserve_vcc 1
		.amdhsa_float_round_mode_32 0
		.amdhsa_float_round_mode_16_64 0
		.amdhsa_float_denorm_mode_32 3
		.amdhsa_float_denorm_mode_16_64 3
		.amdhsa_dx10_clamp 1
		.amdhsa_ieee_mode 1
		.amdhsa_fp16_overflow 0
		.amdhsa_tg_split 0
		.amdhsa_exception_fp_ieee_invalid_op 0
		.amdhsa_exception_fp_denorm_src 0
		.amdhsa_exception_fp_ieee_div_zero 0
		.amdhsa_exception_fp_ieee_overflow 0
		.amdhsa_exception_fp_ieee_underflow 0
		.amdhsa_exception_fp_ieee_inexact 0
		.amdhsa_exception_int_div_zero 0
	.end_amdhsa_kernel

; __global__ void __launch_bounds__(512, 2) hymba_fwd(Params p) {
;   __shared__ __attribute__((aligned(16))) char lds[LDS_BYTES];
;   cg::grid_group grid = cg::this_grid();
;   phase_prep(p, lds);
;   grid.sync();
;   phase_inproj(p, lds);
;   grid.sync();
;   phase_conv(p);
;   grid.sync();
;   phase_mix(p, lds);
;   grid.sync();
;   phase_ssmnorm(p);
;   grid.sync();
;   phase_outproj(p, lds);
;   grid.sync();
;   phase_norm2(p);
;   grid.sync();
;   phase_up(p, lds);
;   grid.sync();
;   phase_down(p, lds);
;   grid.sync();
;   phase_final(p);
; }
amdhsa.kernels:
  - .agpr_count:     0
    .args:
      - .offset:         0
        .size:           200
        .value_kind:     by_value
      - .offset:         200
        .size:           4
        .value_kind:     hidden_block_count_x
      - .offset:         204
        .size:           4
        .value_kind:     hidden_block_count_y
      - .offset:         208
        .size:           4
        .value_kind:     hidden_block_count_z
      - .offset:         212
        .size:           2
        .value_kind:     hidden_group_size_x
      - .offset:         214
        .size:           2
        .value_kind:     hidden_group_size_y
      - .offset:         216
        .size:           2
        .value_kind:     hidden_group_size_z
      - .offset:         218
        .size:           2
        .value_kind:     hidden_remainder_x
      - .offset:         220
        .size:           2
        .value_kind:     hidden_remainder_y
      - .offset:         222
        .size:           2
        .value_kind:     hidden_remainder_z
      - .offset:         240
        .size:           8
        .value_kind:     hidden_global_offset_x
      - .offset:         248
        .size:           8
        .value_kind:     hidden_global_offset_y
      - .offset:         256
        .size:           8
        .value_kind:     hidden_global_offset_z
      - .offset:         264
        .size:           2
        .value_kind:     hidden_grid_dims
      - .offset:         288
        .size:           8
        .value_kind:     hidden_multigrid_sync_arg
    .group_segment_fixed_size: 149760
    .kernarg_segment_align: 8
    .kernarg_segment_size: 456
    .language:       OpenCL C
    .language_version:
      - 2
      - 0
    .max_flat_workgroup_size: 512
    .name:           _Z9hymba_fwd6Params
    .private_segment_fixed_size: 0
    .sgpr_count:     108
    .sgpr_spill_count: 55
    .symbol:         _Z9hymba_fwd6Params.kd
    .uniform_work_group_size: 1
    .uses_dynamic_stack: false
    .vgpr_count:     256
    .vgpr_spill_count: 0
    .wavefront_size: 64
